# GEMM K loop: nothing but MFMAs between the two barriers of an MFMA segment (priority raise and the already-satisfied lgkmcnt wait moved in front of the leading barrier, priority drop behind the traili
# baseline (speedup 1.0000x reference)
.Lgemm_peel:
	s_add_i32 s48, s41, 2
	s_add_u32 s68, s46, 0x80
	s_addc_u32 s69, s47, 0
	s_add_i32 s93, 0, 0x10000
	s_cmp_eq_u32 s20, s41
	s_cselect_b32 s75, s81, s69
	s_cselect_b32 s74, s80, s68
	s_cselect_b32 s79, s77, s39
	s_cselect_b32 s78, s76, s38
	s_add_i32 s41, 0, 0x14000
	v_add_u32_e32 v156, s93, v177
	v_add_u32_e32 v172, s41, v177
	ds_read_b128 v[130:133], v156
	ds_read_b128 v[134:137], v156 offset:1024
	ds_read_b128 v[152:155], v156 offset:2048
	ds_read_b128 v[156:159], v156 offset:3072
	ds_read_b128 v[160:163], v172
	ds_read_b128 v[164:167], v172 offset:1024
	ds_read_b128 v[168:171], v172 offset:2048
	ds_read_b128 v[172:175], v172 offset:3072
	v_lshl_add_u64 v[204:205], s[46:47], 0, v[148:149]
	s_add_i32 m0, s0, 0xc000
	ds_read_b128 v[180:183], v178
	ds_read_b128 v[184:187], v178 offset:1024
	ds_read_b128 v[188:191], v178 offset:2048
	ds_read_b128 v[192:195], v178 offset:3072
	ds_read_b128 v[196:199], v178 offset:4096
	ds_read_b128 v[200:203], v178 offset:5120
	ds_read_b128 v[210:213], v178 offset:6144
	ds_read_b128 v[214:217], v178 offset:7168
	global_load_lds_dwordx4 v[204:205], off
	v_lshl_add_u64 v[204:205], s[46:47], 0, v[150:151]
	s_add_i32 m0, s0, 0xe000
	s_nop 0
	global_load_lds_dwordx4 v[204:205], off
	s_waitcnt vmcnt(8)
	s_waitcnt lgkmcnt(0)
	s_setprio 1
	s_waitcnt lgkmcnt(0)
	s_barrier
	v_mfma_f32_16x16x32_bf16 v[126:129], v[130:133], v[180:183], 0
	v_mfma_f32_16x16x32_bf16 v[122:125], v[152:155], v[180:183], 0
	v_mfma_f32_16x16x32_bf16 v[110:113], v[130:133], v[188:191], 0
	v_mfma_f32_16x16x32_bf16 v[106:109], v[152:155], v[188:191], 0
	v_mfma_f32_16x16x32_bf16 v[94:97], v[130:133], v[196:199], 0
	v_mfma_f32_16x16x32_bf16 v[90:93], v[152:155], v[196:199], 0
	v_mfma_f32_16x16x32_bf16 v[78:81], v[130:133], v[210:213], 0
	v_mfma_f32_16x16x32_bf16 v[74:77], v[152:155], v[210:213], 0
	v_mfma_f32_16x16x32_bf16 v[126:129], v[134:137], v[184:187], v[126:129]
	v_mfma_f32_16x16x32_bf16 v[122:125], v[156:159], v[184:187], v[122:125]
	v_mfma_f32_16x16x32_bf16 v[110:113], v[134:137], v[192:195], v[110:113]
	v_mfma_f32_16x16x32_bf16 v[106:109], v[156:159], v[192:195], v[106:109]
	v_mfma_f32_16x16x32_bf16 v[94:97], v[134:137], v[200:203], v[94:97]
	v_mfma_f32_16x16x32_bf16 v[90:93], v[156:159], v[200:203], v[90:93]
	v_mfma_f32_16x16x32_bf16 v[78:81], v[134:137], v[214:217], v[78:81]
	v_mfma_f32_16x16x32_bf16 v[74:77], v[156:159], v[214:217], v[74:77]
	s_setprio 0
	s_setprio 1
	v_mfma_f32_16x16x32_bf16 v[118:121], v[160:163], v[180:183], 0
	v_mfma_f32_16x16x32_bf16 v[114:117], v[168:171], v[180:183], 0
	v_mfma_f32_16x16x32_bf16 v[102:105], v[160:163], v[188:191], 0
	v_mfma_f32_16x16x32_bf16 v[98:101], v[168:171], v[188:191], 0
	v_mfma_f32_16x16x32_bf16 v[86:89], v[160:163], v[196:199], 0
	v_mfma_f32_16x16x32_bf16 v[82:85], v[168:171], v[196:199], 0
	v_mfma_f32_16x16x32_bf16 v[70:73], v[160:163], v[210:213], 0
	v_mfma_f32_16x16x32_bf16 v[66:69], v[168:171], v[210:213], 0
	v_mfma_f32_16x16x32_bf16 v[118:121], v[164:167], v[184:187], v[118:121]
	v_mfma_f32_16x16x32_bf16 v[114:117], v[172:175], v[184:187], v[114:117]
	v_mfma_f32_16x16x32_bf16 v[102:105], v[164:167], v[192:195], v[102:105]
	v_mfma_f32_16x16x32_bf16 v[98:101], v[172:175], v[192:195], v[98:101]
	v_mfma_f32_16x16x32_bf16 v[86:89], v[164:167], v[200:203], v[86:89]
	v_mfma_f32_16x16x32_bf16 v[82:85], v[172:175], v[200:203], v[82:85]
	v_mfma_f32_16x16x32_bf16 v[70:73], v[164:167], v[214:217], v[70:73]
	v_mfma_f32_16x16x32_bf16 v[66:69], v[172:175], v[214:217], v[66:69]
	s_barrier
	s_setprio 0
	s_add_i32 s68, s93, s91
	v_lshl_add_u64 v[204:205], s[78:79], 0, v[140:141]
	s_mov_b32 m0, s68
	ds_read_b128 v[180:183], v178 offset:16384
	ds_read_b128 v[184:187], v178 offset:17408
	ds_read_b128 v[188:191], v178 offset:18432
	ds_read_b128 v[192:195], v178 offset:19456
	ds_read_b128 v[196:199], v178 offset:20480
	ds_read_b128 v[200:203], v178 offset:21504
	ds_read_b128 v[210:213], v178 offset:22528
	ds_read_b128 v[214:217], v178 offset:23552
	global_load_lds_dwordx4 v[204:205], off
	s_add_i32 m0, s68, 0x2000
	v_lshl_add_u64 v[228:229], s[78:79], 0, v[144:145]
	s_add_u32 s78, s78, s58
	s_addc_u32 s79, s79, 0
	s_add_i32 s41, s41, s91
	global_load_lds_dwordx4 v[228:229], off
	v_lshl_add_u64 v[230:231], s[78:79], 0, v[140:141]
	s_mov_b32 m0, s41
	v_lshl_add_u64 v[232:233], s[78:79], 0, v[144:145]
	global_load_lds_dwordx4 v[230:231], off
	s_add_i32 m0, s41, 0x2000
	v_lshl_add_u64 v[234:235], s[74:75], 0, v[138:139]
	global_load_lds_dwordx4 v[232:233], off
	s_mov_b32 m0, s0
	v_lshl_add_u64 v[236:237], s[74:75], 0, v[142:143]
	global_load_lds_dwordx4 v[234:235], off
	s_mov_b32 m0, s1
	s_nop 0
	global_load_lds_dwordx4 v[236:237], off
	s_waitcnt vmcnt(8)
	s_waitcnt lgkmcnt(0)
	s_setprio 1
	s_waitcnt lgkmcnt(0)
	s_barrier
	v_mfma_f32_16x16x32_bf16 v[62:65], v[130:133], v[180:183], 0
	v_mfma_f32_16x16x32_bf16 v[58:61], v[152:155], v[180:183], 0
	v_mfma_f32_16x16x32_bf16 v[46:49], v[130:133], v[188:191], 0
	v_mfma_f32_16x16x32_bf16 v[42:45], v[152:155], v[188:191], 0
	v_mfma_f32_16x16x32_bf16 v[30:33], v[130:133], v[196:199], 0
	v_mfma_f32_16x16x32_bf16 v[26:29], v[152:155], v[196:199], 0
	v_mfma_f32_16x16x32_bf16 v[14:17], v[130:133], v[210:213], 0
	v_mfma_f32_16x16x32_bf16 v[10:13], v[152:155], v[210:213], 0
	v_mfma_f32_16x16x32_bf16 v[62:65], v[134:137], v[184:187], v[62:65]
	v_mfma_f32_16x16x32_bf16 v[58:61], v[156:159], v[184:187], v[58:61]
	v_mfma_f32_16x16x32_bf16 v[46:49], v[134:137], v[192:195], v[46:49]
	v_mfma_f32_16x16x32_bf16 v[42:45], v[156:159], v[192:195], v[42:45]
	v_mfma_f32_16x16x32_bf16 v[30:33], v[134:137], v[200:203], v[30:33]
	v_mfma_f32_16x16x32_bf16 v[26:29], v[156:159], v[200:203], v[26:29]
	v_mfma_f32_16x16x32_bf16 v[14:17], v[134:137], v[214:217], v[14:17]
	v_mfma_f32_16x16x32_bf16 v[10:13], v[156:159], v[214:217], v[10:13]
	s_setprio 0
	s_setprio 1
	v_mfma_f32_16x16x32_bf16 v[54:57], v[160:163], v[180:183], 0
	v_mfma_f32_16x16x32_bf16 v[50:53], v[168:171], v[180:183], 0
	v_mfma_f32_16x16x32_bf16 v[38:41], v[160:163], v[188:191], 0
	v_mfma_f32_16x16x32_bf16 v[34:37], v[168:171], v[188:191], 0
	v_mfma_f32_16x16x32_bf16 v[22:25], v[160:163], v[196:199], 0
	v_mfma_f32_16x16x32_bf16 v[18:21], v[168:171], v[196:199], 0
	v_mfma_f32_16x16x32_bf16 v[6:9], v[160:163], v[210:213], 0
	v_mfma_f32_16x16x32_bf16 v[2:5], v[168:171], v[210:213], 0
	v_mfma_f32_16x16x32_bf16 v[54:57], v[164:167], v[184:187], v[54:57]
	v_mfma_f32_16x16x32_bf16 v[50:53], v[172:175], v[184:187], v[50:53]
	v_mfma_f32_16x16x32_bf16 v[38:41], v[164:167], v[192:195], v[38:41]
	v_mfma_f32_16x16x32_bf16 v[34:37], v[172:175], v[192:195], v[34:37]
	v_mfma_f32_16x16x32_bf16 v[22:25], v[164:167], v[200:203], v[22:25]
	v_mfma_f32_16x16x32_bf16 v[18:21], v[172:175], v[200:203], v[18:21]
	v_mfma_f32_16x16x32_bf16 v[6:9], v[164:167], v[214:217], v[6:9]
	v_mfma_f32_16x16x32_bf16 v[2:5], v[172:175], v[214:217], v[2:5]
	s_barrier
	s_setprio 0
	s_add_i32 s41, 0, 0x18000
	s_add_i32 s68, 0, 0x1c000
	v_add_u32_e32 v156, s41, v177
	v_add_u32_e32 v172, s68, v177
	ds_read_b128 v[130:133], v156
	ds_read_b128 v[134:137], v156 offset:1024
	ds_read_b128 v[152:155], v156 offset:2048
	ds_read_b128 v[156:159], v156 offset:3072
	ds_read_b128 v[160:163], v172
	ds_read_b128 v[164:167], v172 offset:1024
	ds_read_b128 v[168:171], v172 offset:2048
	ds_read_b128 v[172:175], v172 offset:3072
	s_add_u32 s74, s74, s58
	s_addc_u32 s75, s75, 0
	s_mov_b32 m0, s72
	v_lshl_add_u64 v[238:239], s[74:75], 0, v[138:139]
	ds_read_b128 v[180:183], v178 offset:32768
	ds_read_b128 v[184:187], v178 offset:33792
	ds_read_b128 v[188:191], v178 offset:34816
	ds_read_b128 v[192:195], v178 offset:35840
	ds_read_b128 v[196:199], v178 offset:36864
	ds_read_b128 v[200:203], v178 offset:37888
	ds_read_b128 v[210:213], v178 offset:38912
	ds_read_b128 v[214:217], v178 offset:39936
	global_load_lds_dwordx4 v[238:239], off
	v_lshl_add_u64 v[238:239], s[74:75], 0, v[142:143]
	s_mov_b32 m0, s73
	s_nop 0
	global_load_lds_dwordx4 v[238:239], off
	s_waitcnt vmcnt(8)
	s_waitcnt lgkmcnt(0)
	s_setprio 1
	s_waitcnt lgkmcnt(0)
	s_barrier
	v_mfma_f32_16x16x32_bf16 v[126:129], v[130:133], v[180:183], v[126:129]
	v_mfma_f32_16x16x32_bf16 v[122:125], v[152:155], v[180:183], v[122:125]
	v_mfma_f32_16x16x32_bf16 v[110:113], v[130:133], v[188:191], v[110:113]
	v_mfma_f32_16x16x32_bf16 v[106:109], v[152:155], v[188:191], v[106:109]
	v_mfma_f32_16x16x32_bf16 v[94:97], v[130:133], v[196:199], v[94:97]
	v_mfma_f32_16x16x32_bf16 v[90:93], v[152:155], v[196:199], v[90:93]
	v_mfma_f32_16x16x32_bf16 v[78:81], v[130:133], v[210:213], v[78:81]
	v_mfma_f32_16x16x32_bf16 v[74:77], v[152:155], v[210:213], v[74:77]
	v_mfma_f32_16x16x32_bf16 v[126:129], v[134:137], v[184:187], v[126:129]
	v_mfma_f32_16x16x32_bf16 v[122:125], v[156:159], v[184:187], v[122:125]
	v_mfma_f32_16x16x32_bf16 v[110:113], v[134:137], v[192:195], v[110:113]
	v_mfma_f32_16x16x32_bf16 v[106:109], v[156:159], v[192:195], v[106:109]
	v_mfma_f32_16x16x32_bf16 v[94:97], v[134:137], v[200:203], v[94:97]
	v_mfma_f32_16x16x32_bf16 v[90:93], v[156:159], v[200:203], v[90:93]
	v_mfma_f32_16x16x32_bf16 v[78:81], v[134:137], v[214:217], v[78:81]
	v_mfma_f32_16x16x32_bf16 v[74:77], v[156:159], v[214:217], v[74:77]
	s_setprio 0
	s_setprio 1
	v_mfma_f32_16x16x32_bf16 v[118:121], v[160:163], v[180:183], v[118:121]
	v_mfma_f32_16x16x32_bf16 v[114:117], v[168:171], v[180:183], v[114:117]
	v_mfma_f32_16x16x32_bf16 v[102:105], v[160:163], v[188:191], v[102:105]
	v_mfma_f32_16x16x32_bf16 v[98:101], v[168:171], v[188:191], v[98:101]
	v_mfma_f32_16x16x32_bf16 v[86:89], v[160:163], v[196:199], v[86:89]
	v_mfma_f32_16x16x32_bf16 v[82:85], v[168:171], v[196:199], v[82:85]
	v_mfma_f32_16x16x32_bf16 v[70:73], v[160:163], v[210:213], v[70:73]
	v_mfma_f32_16x16x32_bf16 v[66:69], v[168:171], v[210:213], v[66:69]
	v_mfma_f32_16x16x32_bf16 v[118:121], v[164:167], v[184:187], v[118:121]
	v_mfma_f32_16x16x32_bf16 v[114:117], v[172:175], v[184:187], v[114:117]
	v_mfma_f32_16x16x32_bf16 v[102:105], v[164:167], v[192:195], v[102:105]
	v_mfma_f32_16x16x32_bf16 v[98:101], v[172:175], v[192:195], v[98:101]
	v_mfma_f32_16x16x32_bf16 v[86:89], v[164:167], v[200:203], v[86:89]
	v_mfma_f32_16x16x32_bf16 v[82:85], v[172:175], v[200:203], v[82:85]
	v_mfma_f32_16x16x32_bf16 v[70:73], v[164:167], v[214:217], v[70:73]
	v_mfma_f32_16x16x32_bf16 v[66:69], v[172:175], v[214:217], v[66:69]
	s_barrier
	s_setprio 0
	s_add_i32 s41, s41, s91
	v_lshl_add_u64 v[204:205], v[204:205], 0, s[18:19]
	s_mov_b32 m0, s41
	ds_read_b128 v[180:183], v178 offset:49152
	ds_read_b128 v[184:187], v178 offset:50176
	ds_read_b128 v[188:191], v178 offset:51200
	ds_read_b128 v[192:195], v178 offset:52224
	ds_read_b128 v[196:199], v178 offset:53248
	ds_read_b128 v[200:203], v178 offset:54272
	ds_read_b128 v[210:213], v178 offset:55296
	ds_read_b128 v[214:217], v178 offset:56320
	global_load_lds_dwordx4 v[204:205], off
	v_lshl_add_u64 v[204:205], v[228:229], 0, s[18:19]
	s_add_i32 m0, s41, 0x2000
	s_add_i32 s41, s68, s91
	global_load_lds_dwordx4 v[204:205], off
	v_lshl_add_u64 v[204:205], v[230:231], 0, s[18:19]
	s_mov_b32 m0, s41
	s_nop 0
	global_load_lds_dwordx4 v[204:205], off
	v_lshl_add_u64 v[204:205], v[232:233], 0, s[18:19]
	s_add_i32 m0, s41, 0x2000
	s_nop 0
	global_load_lds_dwordx4 v[204:205], off
	v_lshl_add_u64 v[204:205], v[234:235], 0, s[18:19]
	s_mov_b32 m0, s27
	s_nop 0
	global_load_lds_dwordx4 v[204:205], off
	v_lshl_add_u64 v[204:205], v[236:237], 0, s[18:19]
	s_mov_b32 m0, s25
	s_nop 0
	global_load_lds_dwordx4 v[204:205], off
	s_waitcnt vmcnt(8)
	s_waitcnt lgkmcnt(0)
	s_setprio 1
	s_waitcnt lgkmcnt(0)
	s_barrier
	v_mfma_f32_16x16x32_bf16 v[62:65], v[130:133], v[180:183], v[62:65]
	v_mfma_f32_16x16x32_bf16 v[58:61], v[152:155], v[180:183], v[58:61]
	v_mfma_f32_16x16x32_bf16 v[46:49], v[130:133], v[188:191], v[46:49]
	v_mfma_f32_16x16x32_bf16 v[42:45], v[152:155], v[188:191], v[42:45]
	v_mfma_f32_16x16x32_bf16 v[30:33], v[130:133], v[196:199], v[30:33]
	v_mfma_f32_16x16x32_bf16 v[26:29], v[152:155], v[196:199], v[26:29]
	v_mfma_f32_16x16x32_bf16 v[14:17], v[130:133], v[210:213], v[14:17]
	v_mfma_f32_16x16x32_bf16 v[10:13], v[152:155], v[210:213], v[10:13]
	v_mfma_f32_16x16x32_bf16 v[62:65], v[134:137], v[184:187], v[62:65]
	v_mfma_f32_16x16x32_bf16 v[58:61], v[156:159], v[184:187], v[58:61]
	v_mfma_f32_16x16x32_bf16 v[46:49], v[134:137], v[192:195], v[46:49]
	v_mfma_f32_16x16x32_bf16 v[42:45], v[156:159], v[192:195], v[42:45]
	v_mfma_f32_16x16x32_bf16 v[30:33], v[134:137], v[200:203], v[30:33]
	v_mfma_f32_16x16x32_bf16 v[26:29], v[156:159], v[200:203], v[26:29]
	v_mfma_f32_16x16x32_bf16 v[14:17], v[134:137], v[214:217], v[14:17]
	v_mfma_f32_16x16x32_bf16 v[10:13], v[156:159], v[214:217], v[10:13]
	s_setprio 0
	s_setprio 1
	v_mfma_f32_16x16x32_bf16 v[54:57], v[160:163], v[180:183], v[54:57]
	v_mfma_f32_16x16x32_bf16 v[50:53], v[168:171], v[180:183], v[50:53]
	v_mfma_f32_16x16x32_bf16 v[38:41], v[160:163], v[188:191], v[38:41]
	v_mfma_f32_16x16x32_bf16 v[34:37], v[168:171], v[188:191], v[34:37]
	v_mfma_f32_16x16x32_bf16 v[22:25], v[160:163], v[196:199], v[22:25]
	v_mfma_f32_16x16x32_bf16 v[18:21], v[168:171], v[196:199], v[18:21]
	v_mfma_f32_16x16x32_bf16 v[6:9], v[160:163], v[210:213], v[6:9]
	v_mfma_f32_16x16x32_bf16 v[2:5], v[168:171], v[210:213], v[2:5]
	v_mfma_f32_16x16x32_bf16 v[54:57], v[164:167], v[184:187], v[54:57]
	v_mfma_f32_16x16x32_bf16 v[50:53], v[172:175], v[184:187], v[50:53]
	v_mfma_f32_16x16x32_bf16 v[38:41], v[164:167], v[192:195], v[38:41]
	v_mfma_f32_16x16x32_bf16 v[34:37], v[172:175], v[192:195], v[34:37]
	v_mfma_f32_16x16x32_bf16 v[22:25], v[164:167], v[200:203], v[22:25]
	v_mfma_f32_16x16x32_bf16 v[18:21], v[172:175], v[200:203], v[18:21]
	v_mfma_f32_16x16x32_bf16 v[6:9], v[164:167], v[214:217], v[6:9]
	v_mfma_f32_16x16x32_bf16 v[2:5], v[172:175], v[214:217], v[2:5]
	s_barrier
	s_setprio 0
	s_add_u32 s46, s46, 0x100
	s_addc_u32 s47, s47, 0
	s_add_u32 s38, s38, 0x100
	s_addc_u32 s39, s39, 0
	s_cmp_ge_u32 s48, s50
	s_mov_b32 s41, s48
	s_cbranch_scc1 .LBB0_433
.LBB0_432:
	s_add_i32 s48, s41, 2
	s_add_u32 s68, s46, 0x80
	s_addc_u32 s69, s47, 0
	s_add_i32 s93, 0, 0x10000
	s_cmp_eq_u32 s20, s41
	s_cselect_b32 s75, s81, s69
	s_cselect_b32 s74, s80, s68
	s_cselect_b32 s79, s77, s39
	s_cselect_b32 s78, s76, s38
	s_add_i32 s41, 0, 0x14000
	v_add_u32_e32 v156, s93, v177
	v_add_u32_e32 v172, s41, v177
	ds_read_b128 v[130:133], v156
	ds_read_b128 v[134:137], v156 offset:1024
	ds_read_b128 v[152:155], v156 offset:2048
	ds_read_b128 v[156:159], v156 offset:3072
	ds_read_b128 v[160:163], v172
	ds_read_b128 v[164:167], v172 offset:1024
	ds_read_b128 v[168:171], v172 offset:2048
	ds_read_b128 v[172:175], v172 offset:3072
	v_lshl_add_u64 v[204:205], s[46:47], 0, v[148:149]
	s_add_i32 m0, s0, 0xc000
	ds_read_b128 v[180:183], v178
	ds_read_b128 v[184:187], v178 offset:1024
	ds_read_b128 v[188:191], v178 offset:2048
	ds_read_b128 v[192:195], v178 offset:3072
	ds_read_b128 v[196:199], v178 offset:4096
	ds_read_b128 v[200:203], v178 offset:5120
	ds_read_b128 v[210:213], v178 offset:6144
	ds_read_b128 v[214:217], v178 offset:7168
	global_load_lds_dwordx4 v[204:205], off
	v_lshl_add_u64 v[204:205], s[46:47], 0, v[150:151]
	s_add_i32 m0, s0, 0xe000
	s_nop 0
	global_load_lds_dwordx4 v[204:205], off
	s_waitcnt vmcnt(8)
	s_waitcnt lgkmcnt(0)
	s_setprio 1
	s_waitcnt lgkmcnt(0)
	s_barrier
	v_mfma_f32_16x16x32_bf16 v[126:129], v[130:133], v[180:183], v[126:129]
	v_mfma_f32_16x16x32_bf16 v[122:125], v[152:155], v[180:183], v[122:125]
	v_mfma_f32_16x16x32_bf16 v[110:113], v[130:133], v[188:191], v[110:113]
	v_mfma_f32_16x16x32_bf16 v[106:109], v[152:155], v[188:191], v[106:109]
	v_mfma_f32_16x16x32_bf16 v[94:97], v[130:133], v[196:199], v[94:97]
	v_mfma_f32_16x16x32_bf16 v[90:93], v[152:155], v[196:199], v[90:93]
	v_mfma_f32_16x16x32_bf16 v[78:81], v[130:133], v[210:213], v[78:81]
	v_mfma_f32_16x16x32_bf16 v[74:77], v[152:155], v[210:213], v[74:77]
	v_mfma_f32_16x16x32_bf16 v[126:129], v[134:137], v[184:187], v[126:129]
	v_mfma_f32_16x16x32_bf16 v[122:125], v[156:159], v[184:187], v[122:125]
	v_mfma_f32_16x16x32_bf16 v[110:113], v[134:137], v[192:195], v[110:113]
	v_mfma_f32_16x16x32_bf16 v[106:109], v[156:159], v[192:195], v[106:109]
	v_mfma_f32_16x16x32_bf16 v[94:97], v[134:137], v[200:203], v[94:97]
	v_mfma_f32_16x16x32_bf16 v[90:93], v[156:159], v[200:203], v[90:93]
	v_mfma_f32_16x16x32_bf16 v[78:81], v[134:137], v[214:217], v[78:81]
	v_mfma_f32_16x16x32_bf16 v[74:77], v[156:159], v[214:217], v[74:77]
	s_setprio 0
	s_setprio 1
	v_mfma_f32_16x16x32_bf16 v[118:121], v[160:163], v[180:183], v[118:121]
	v_mfma_f32_16x16x32_bf16 v[114:117], v[168:171], v[180:183], v[114:117]
	v_mfma_f32_16x16x32_bf16 v[102:105], v[160:163], v[188:191], v[102:105]
	v_mfma_f32_16x16x32_bf16 v[98:101], v[168:171], v[188:191], v[98:101]
	v_mfma_f32_16x16x32_bf16 v[86:89], v[160:163], v[196:199], v[86:89]
	v_mfma_f32_16x16x32_bf16 v[82:85], v[168:171], v[196:199], v[82:85]
	v_mfma_f32_16x16x32_bf16 v[70:73], v[160:163], v[210:213], v[70:73]
	v_mfma_f32_16x16x32_bf16 v[66:69], v[168:171], v[210:213], v[66:69]
	v_mfma_f32_16x16x32_bf16 v[118:121], v[164:167], v[184:187], v[118:121]
	v_mfma_f32_16x16x32_bf16 v[114:117], v[172:175], v[184:187], v[114:117]
	v_mfma_f32_16x16x32_bf16 v[102:105], v[164:167], v[192:195], v[102:105]
	v_mfma_f32_16x16x32_bf16 v[98:101], v[172:175], v[192:195], v[98:101]
	v_mfma_f32_16x16x32_bf16 v[86:89], v[164:167], v[200:203], v[86:89]
	v_mfma_f32_16x16x32_bf16 v[82:85], v[172:175], v[200:203], v[82:85]
	v_mfma_f32_16x16x32_bf16 v[70:73], v[164:167], v[214:217], v[70:73]
	v_mfma_f32_16x16x32_bf16 v[66:69], v[172:175], v[214:217], v[66:69]
	s_barrier
	s_setprio 0
	s_add_i32 s68, s93, s91
	v_lshl_add_u64 v[204:205], s[78:79], 0, v[140:141]
	s_mov_b32 m0, s68
	ds_read_b128 v[180:183], v178 offset:16384
	ds_read_b128 v[184:187], v178 offset:17408
	ds_read_b128 v[188:191], v178 offset:18432
	ds_read_b128 v[192:195], v178 offset:19456
	ds_read_b128 v[196:199], v178 offset:20480
	ds_read_b128 v[200:203], v178 offset:21504
	ds_read_b128 v[210:213], v178 offset:22528
	ds_read_b128 v[214:217], v178 offset:23552
	global_load_lds_dwordx4 v[204:205], off
	s_add_i32 m0, s68, 0x2000
	v_lshl_add_u64 v[228:229], s[78:79], 0, v[144:145]
	s_add_u32 s78, s78, s58
	s_addc_u32 s79, s79, 0
	s_add_i32 s41, s41, s91
	global_load_lds_dwordx4 v[228:229], off
	v_lshl_add_u64 v[230:231], s[78:79], 0, v[140:141]
	s_mov_b32 m0, s41
	v_lshl_add_u64 v[232:233], s[78:79], 0, v[144:145]
	global_load_lds_dwordx4 v[230:231], off
	s_add_i32 m0, s41, 0x2000
	v_lshl_add_u64 v[234:235], s[74:75], 0, v[138:139]
	global_load_lds_dwordx4 v[232:233], off
	s_mov_b32 m0, s0
	v_lshl_add_u64 v[236:237], s[74:75], 0, v[142:143]
	global_load_lds_dwordx4 v[234:235], off
	s_mov_b32 m0, s1
	s_nop 0
	global_load_lds_dwordx4 v[236:237], off
	s_waitcnt vmcnt(8)
	s_waitcnt lgkmcnt(0)
	s_setprio 1
	s_waitcnt lgkmcnt(0)
	s_barrier
	v_mfma_f32_16x16x32_bf16 v[62:65], v[130:133], v[180:183], v[62:65]
	v_mfma_f32_16x16x32_bf16 v[58:61], v[152:155], v[180:183], v[58:61]
	v_mfma_f32_16x16x32_bf16 v[46:49], v[130:133], v[188:191], v[46:49]
	v_mfma_f32_16x16x32_bf16 v[42:45], v[152:155], v[188:191], v[42:45]
	v_mfma_f32_16x16x32_bf16 v[30:33], v[130:133], v[196:199], v[30:33]
	v_mfma_f32_16x16x32_bf16 v[26:29], v[152:155], v[196:199], v[26:29]
	v_mfma_f32_16x16x32_bf16 v[14:17], v[130:133], v[210:213], v[14:17]
	v_mfma_f32_16x16x32_bf16 v[10:13], v[152:155], v[210:213], v[10:13]
	v_mfma_f32_16x16x32_bf16 v[62:65], v[134:137], v[184:187], v[62:65]
	v_mfma_f32_16x16x32_bf16 v[58:61], v[156:159], v[184:187], v[58:61]
	v_mfma_f32_16x16x32_bf16 v[46:49], v[134:137], v[192:195], v[46:49]
	v_mfma_f32_16x16x32_bf16 v[42:45], v[156:159], v[192:195], v[42:45]
	v_mfma_f32_16x16x32_bf16 v[30:33], v[134:137], v[200:203], v[30:33]
	v_mfma_f32_16x16x32_bf16 v[26:29], v[156:159], v[200:203], v[26:29]
	v_mfma_f32_16x16x32_bf16 v[14:17], v[134:137], v[214:217], v[14:17]
	v_mfma_f32_16x16x32_bf16 v[10:13], v[156:159], v[214:217], v[10:13]
	s_setprio 0
	s_setprio 1
	v_mfma_f32_16x16x32_bf16 v[54:57], v[160:163], v[180:183], v[54:57]
	v_mfma_f32_16x16x32_bf16 v[50:53], v[168:171], v[180:183], v[50:53]
	v_mfma_f32_16x16x32_bf16 v[38:41], v[160:163], v[188:191], v[38:41]
	v_mfma_f32_16x16x32_bf16 v[34:37], v[168:171], v[188:191], v[34:37]
	v_mfma_f32_16x16x32_bf16 v[22:25], v[160:163], v[196:199], v[22:25]
	v_mfma_f32_16x16x32_bf16 v[18:21], v[168:171], v[196:199], v[18:21]
	v_mfma_f32_16x16x32_bf16 v[6:9], v[160:163], v[210:213], v[6:9]
	v_mfma_f32_16x16x32_bf16 v[2:5], v[168:171], v[210:213], v[2:5]
	v_mfma_f32_16x16x32_bf16 v[54:57], v[164:167], v[184:187], v[54:57]
	v_mfma_f32_16x16x32_bf16 v[50:53], v[172:175], v[184:187], v[50:53]
	v_mfma_f32_16x16x32_bf16 v[38:41], v[164:167], v[192:195], v[38:41]
	v_mfma_f32_16x16x32_bf16 v[34:37], v[172:175], v[192:195], v[34:37]
	v_mfma_f32_16x16x32_bf16 v[22:25], v[164:167], v[200:203], v[22:25]
	v_mfma_f32_16x16x32_bf16 v[18:21], v[172:175], v[200:203], v[18:21]
	v_mfma_f32_16x16x32_bf16 v[6:9], v[164:167], v[214:217], v[6:9]
	v_mfma_f32_16x16x32_bf16 v[2:5], v[172:175], v[214:217], v[2:5]
	s_barrier
	s_setprio 0
	s_add_i32 s41, 0, 0x18000
	s_add_i32 s68, 0, 0x1c000
	v_add_u32_e32 v156, s41, v177
	v_add_u32_e32 v172, s68, v177
	ds_read_b128 v[130:133], v156
	ds_read_b128 v[134:137], v156 offset:1024
	ds_read_b128 v[152:155], v156 offset:2048
	ds_read_b128 v[156:159], v156 offset:3072
	ds_read_b128 v[160:163], v172
	ds_read_b128 v[164:167], v172 offset:1024
	ds_read_b128 v[168:171], v172 offset:2048
	ds_read_b128 v[172:175], v172 offset:3072
	s_add_u32 s74, s74, s58
	s_addc_u32 s75, s75, 0
	s_mov_b32 m0, s72
	v_lshl_add_u64 v[238:239], s[74:75], 0, v[138:139]
	ds_read_b128 v[180:183], v178 offset:32768
	ds_read_b128 v[184:187], v178 offset:33792
	ds_read_b128 v[188:191], v178 offset:34816
	ds_read_b128 v[192:195], v178 offset:35840
	ds_read_b128 v[196:199], v178 offset:36864
	ds_read_b128 v[200:203], v178 offset:37888
	ds_read_b128 v[210:213], v178 offset:38912
	ds_read_b128 v[214:217], v178 offset:39936
	global_load_lds_dwordx4 v[238:239], off
	v_lshl_add_u64 v[238:239], s[74:75], 0, v[142:143]
	s_mov_b32 m0, s73
	s_nop 0
	global_load_lds_dwordx4 v[238:239], off
	s_waitcnt vmcnt(8)
	s_waitcnt lgkmcnt(0)
	s_setprio 1
	s_waitcnt lgkmcnt(0)
	s_barrier
	v_mfma_f32_16x16x32_bf16 v[126:129], v[130:133], v[180:183], v[126:129]
	v_mfma_f32_16x16x32_bf16 v[122:125], v[152:155], v[180:183], v[122:125]
	v_mfma_f32_16x16x32_bf16 v[110:113], v[130:133], v[188:191], v[110:113]
	v_mfma_f32_16x16x32_bf16 v[106:109], v[152:155], v[188:191], v[106:109]
	v_mfma_f32_16x16x32_bf16 v[94:97], v[130:133], v[196:199], v[94:97]
	v_mfma_f32_16x16x32_bf16 v[90:93], v[152:155], v[196:199], v[90:93]
	v_mfma_f32_16x16x32_bf16 v[78:81], v[130:133], v[210:213], v[78:81]
	v_mfma_f32_16x16x32_bf16 v[74:77], v[152:155], v[210:213], v[74:77]
	v_mfma_f32_16x16x32_bf16 v[126:129], v[134:137], v[184:187], v[126:129]
	v_mfma_f32_16x16x32_bf16 v[122:125], v[156:159], v[184:187], v[122:125]
	v_mfma_f32_16x16x32_bf16 v[110:113], v[134:137], v[192:195], v[110:113]
	v_mfma_f32_16x16x32_bf16 v[106:109], v[156:159], v[192:195], v[106:109]
	v_mfma_f32_16x16x32_bf16 v[94:97], v[134:137], v[200:203], v[94:97]
	v_mfma_f32_16x16x32_bf16 v[90:93], v[156:159], v[200:203], v[90:93]
	v_mfma_f32_16x16x32_bf16 v[78:81], v[134:137], v[214:217], v[78:81]
	v_mfma_f32_16x16x32_bf16 v[74:77], v[156:159], v[214:217], v[74:77]
	s_setprio 0
	s_setprio 1
	v_mfma_f32_16x16x32_bf16 v[118:121], v[160:163], v[180:183], v[118:121]
	v_mfma_f32_16x16x32_bf16 v[114:117], v[168:171], v[180:183], v[114:117]
	v_mfma_f32_16x16x32_bf16 v[102:105], v[160:163], v[188:191], v[102:105]
	v_mfma_f32_16x16x32_bf16 v[98:101], v[168:171], v[188:191], v[98:101]
	v_mfma_f32_16x16x32_bf16 v[86:89], v[160:163], v[196:199], v[86:89]
	v_mfma_f32_16x16x32_bf16 v[82:85], v[168:171], v[196:199], v[82:85]
	v_mfma_f32_16x16x32_bf16 v[70:73], v[160:163], v[210:213], v[70:73]
	v_mfma_f32_16x16x32_bf16 v[66:69], v[168:171], v[210:213], v[66:69]
	v_mfma_f32_16x16x32_bf16 v[118:121], v[164:167], v[184:187], v[118:121]
	v_mfma_f32_16x16x32_bf16 v[114:117], v[172:175], v[184:187], v[114:117]
	v_mfma_f32_16x16x32_bf16 v[102:105], v[164:167], v[192:195], v[102:105]
	v_mfma_f32_16x16x32_bf16 v[98:101], v[172:175], v[192:195], v[98:101]
	v_mfma_f32_16x16x32_bf16 v[86:89], v[164:167], v[200:203], v[86:89]
	v_mfma_f32_16x16x32_bf16 v[82:85], v[172:175], v[200:203], v[82:85]
	v_mfma_f32_16x16x32_bf16 v[70:73], v[164:167], v[214:217], v[70:73]
	v_mfma_f32_16x16x32_bf16 v[66:69], v[172:175], v[214:217], v[66:69]
	s_barrier
	s_setprio 0
	s_add_i32 s41, s41, s91
	v_lshl_add_u64 v[204:205], v[204:205], 0, s[18:19]
	s_mov_b32 m0, s41
	ds_read_b128 v[180:183], v178 offset:49152
	ds_read_b128 v[184:187], v178 offset:50176
	ds_read_b128 v[188:191], v178 offset:51200
	ds_read_b128 v[192:195], v178 offset:52224
	ds_read_b128 v[196:199], v178 offset:53248
	ds_read_b128 v[200:203], v178 offset:54272
	ds_read_b128 v[210:213], v178 offset:55296
	ds_read_b128 v[214:217], v178 offset:56320
	global_load_lds_dwordx4 v[204:205], off
	v_lshl_add_u64 v[204:205], v[228:229], 0, s[18:19]
	s_add_i32 m0, s41, 0x2000
	s_add_i32 s41, s68, s91
	global_load_lds_dwordx4 v[204:205], off
	v_lshl_add_u64 v[204:205], v[230:231], 0, s[18:19]
	s_mov_b32 m0, s41
	s_nop 0
	global_load_lds_dwordx4 v[204:205], off
	v_lshl_add_u64 v[204:205], v[232:233], 0, s[18:19]
	s_add_i32 m0, s41, 0x2000
	s_nop 0
	global_load_lds_dwordx4 v[204:205], off
	v_lshl_add_u64 v[204:205], v[234:235], 0, s[18:19]
	s_mov_b32 m0, s27
	s_nop 0
	global_load_lds_dwordx4 v[204:205], off
	v_lshl_add_u64 v[204:205], v[236:237], 0, s[18:19]
	s_mov_b32 m0, s25
	s_nop 0
	global_load_lds_dwordx4 v[204:205], off
	s_waitcnt vmcnt(8)
	s_waitcnt lgkmcnt(0)
	s_setprio 1
	s_waitcnt lgkmcnt(0)
	s_barrier
	v_mfma_f32_16x16x32_bf16 v[62:65], v[130:133], v[180:183], v[62:65]
	v_mfma_f32_16x16x32_bf16 v[58:61], v[152:155], v[180:183], v[58:61]
	v_mfma_f32_16x16x32_bf16 v[46:49], v[130:133], v[188:191], v[46:49]
	v_mfma_f32_16x16x32_bf16 v[42:45], v[152:155], v[188:191], v[42:45]
	v_mfma_f32_16x16x32_bf16 v[30:33], v[130:133], v[196:199], v[30:33]
	v_mfma_f32_16x16x32_bf16 v[26:29], v[152:155], v[196:199], v[26:29]
	v_mfma_f32_16x16x32_bf16 v[14:17], v[130:133], v[210:213], v[14:17]
	v_mfma_f32_16x16x32_bf16 v[10:13], v[152:155], v[210:213], v[10:13]
	v_mfma_f32_16x16x32_bf16 v[62:65], v[134:137], v[184:187], v[62:65]
	v_mfma_f32_16x16x32_bf16 v[58:61], v[156:159], v[184:187], v[58:61]
	v_mfma_f32_16x16x32_bf16 v[46:49], v[134:137], v[192:195], v[46:49]
	v_mfma_f32_16x16x32_bf16 v[42:45], v[156:159], v[192:195], v[42:45]
	v_mfma_f32_16x16x32_bf16 v[30:33], v[134:137], v[200:203], v[30:33]
	v_mfma_f32_16x16x32_bf16 v[26:29], v[156:159], v[200:203], v[26:29]
	v_mfma_f32_16x16x32_bf16 v[14:17], v[134:137], v[214:217], v[14:17]
	v_mfma_f32_16x16x32_bf16 v[10:13], v[156:159], v[214:217], v[10:13]
	s_setprio 0
	s_setprio 1
	v_mfma_f32_16x16x32_bf16 v[54:57], v[160:163], v[180:183], v[54:57]
	v_mfma_f32_16x16x32_bf16 v[50:53], v[168:171], v[180:183], v[50:53]
	v_mfma_f32_16x16x32_bf16 v[38:41], v[160:163], v[188:191], v[38:41]
	v_mfma_f32_16x16x32_bf16 v[34:37], v[168:171], v[188:191], v[34:37]
	v_mfma_f32_16x16x32_bf16 v[22:25], v[160:163], v[196:199], v[22:25]
	v_mfma_f32_16x16x32_bf16 v[18:21], v[168:171], v[196:199], v[18:21]
	v_mfma_f32_16x16x32_bf16 v[6:9], v[160:163], v[210:213], v[6:9]
	v_mfma_f32_16x16x32_bf16 v[2:5], v[168:171], v[210:213], v[2:5]
	v_mfma_f32_16x16x32_bf16 v[54:57], v[164:167], v[184:187], v[54:57]
	v_mfma_f32_16x16x32_bf16 v[50:53], v[172:175], v[184:187], v[50:53]
	v_mfma_f32_16x16x32_bf16 v[38:41], v[164:167], v[192:195], v[38:41]
	v_mfma_f32_16x16x32_bf16 v[34:37], v[172:175], v[192:195], v[34:37]
	v_mfma_f32_16x16x32_bf16 v[22:25], v[164:167], v[200:203], v[22:25]
	v_mfma_f32_16x16x32_bf16 v[18:21], v[172:175], v[200:203], v[18:21]
	v_mfma_f32_16x16x32_bf16 v[6:9], v[164:167], v[214:217], v[6:9]
	v_mfma_f32_16x16x32_bf16 v[2:5], v[172:175], v[214:217], v[2:5]
	s_barrier
	s_setprio 0
	s_add_u32 s46, s46, 0x100
	s_addc_u32 s47, s47, 0
	s_add_u32 s38, s38, 0x100
	s_addc_u32 s39, s39, 0
	s_cmp_ge_u32 s48, s50
	s_mov_b32 s41, s48
	s_cbranch_scc0 .LBB0_432
